# attention tasks rebalanced away from the carry-scan workgroups
# speedup vs baseline: 1.0327x; 1.0039x over previous
; __device__ __forceinline__ int opaque_tid() { int t = threadIdx.x; asm volatile("" : "+v"(t)); return t; }
; __device__ void attn_phase(PP p, int layer) {
;     const int tid = opaque_tid(), wid = tid >> 6, lane = tid & 63, qi = lane & 15, quad = lane >> 4;
;     const bf16_t* PROJ = (const bf16_t*)(p->ws + WS_PROJ); const bf16_t* VT = (const bf16_t*)(p->ws + WS_VT); bf16_t* U = (bf16_t*)(p->ws + WS_U);
;     const int ntask = 8192 + (layer < 3 ? 512 : 0);
;     for (int task = blockIdx.x * 8 + wid; task < ntask; task += gridDim.x * 8) {
;         int b, head, tq0, nband, r = 0, ct = 0, rs = 0, cs = 0;
;         if (task < 8192) { ct = task & 3; r = (task >> 2) & 63; head = (task >> 8) & 7; b = task >> 11; tq0 = b * SEQ + r * 64 + ct * 16;
;             rs = min(max(r - 4, 0), 56); cs = min(max(ct * 16 - 8, 0), 32); nband = 8; }
;         else { const int t2 = task - 8192; head = (t2 >> 4) & 7; b = t2 >> 7; tq0 = TLAT + b * NCTX + (t2 & 15) * 16; nband = 0; }
;         const bf16_t* qp = PROJ + (size_t)(tq0 + qi) * NIN + head * 64 + quad * 8;
;         const bf16x8 qf0 = *(const bf16x8*)qp, qf1 = *(const bf16x8*)(qp + 32);
.LBB0_358:
	s_or_b64 exec, exec, s[8:9]
	v_mov_b32_e32 v0, v160
	s_load_dwordx2 s[6:7], s[0:1], 0xd0
	s_mov_b32 s41, s65
	v_ashrrev_i32_e32 v1, 6, v0
	s_movk_i32 s4, 0x2200
	s_waitcnt lgkmcnt(0)
	s_add_u32 s64, s6, 0x19898000
	s_addc_u32 s65, s7, 0
	s_add_u32 s48, s6, 0x3e698000
	s_addc_u32 s49, s7, 0
	v_readlane_b32 s6, v249, 63
	s_cmp_lt_i32 s6, 3
	v_readlane_b32 s7, v248, 0
	s_cselect_b64 s[38:39], -1, 0
	s_and_b64 s[6:7], s[38:39], exec
	v_readlane_b32 s6, v249, 25
	s_cselect_b32 s4, s4, 0x2000
	s_cmpk_gt_u32 s2, 0xdf
	s_cselect_b32 s4, 0x1800, s4
	s_mul_i32 s7, s2, 6
	s_addk_i32 s7, 0x180
	s_sub_i32 vcc_lo, s2, 64
	s_cmpk_lt_u32 vcc_lo, 0x80
	s_cselect_b32 s7, s7, 0
	v_cmp_gt_u32_e32 vcc, 2, v1
	s_nop 1
	v_mov_b32_e32 v230, s7
	v_cndmask_b32_e32 v230, 0, v230, vcc
	v_add_u32_e32 v89, s6, v1
	v_cmp_gt_i32_e32 vcc, s4, v89
	s_and_saveexec_b64 s[50:51], vcc
	s_cbranch_execz .LBB0_403
	s_load_dwordx2 s[6:7], s[0:1], 0xd0
	v_bfe_u32 v2, v0, 4, 2
	v_and_b32_e32 v88, 15, v0
	v_lshlrev_b32_e32 v1, 1, v0
	v_and_b32_e32 v0, 3, v0
	v_lshlrev_b32_e32 v162, 4, v2
	v_and_or_b32 v91, v1, 24, v0
	s_waitcnt lgkmcnt(0)
	v_lshl_add_u64 v[0:1], s[6:7], 0, v[162:163]
	s_mov_b64 s[6:7], 0x37498000
	v_lshl_add_u64 v[92:93], v[0:1], 0, s[6:7]
	v_mbcnt_hi_u32_b32 v0, -1, v197
	v_and_b32_e32 v3, 64, v0
	v_xor_b32_e32 v1, 16, v0
	v_add_u32_e32 v4, 64, v3
	v_cmp_lt_i32_e32 vcc, v1, v4
	v_lshlrev_b32_e32 v139, 2, v2
	s_and_b32 s34, s41, -8
	v_cndmask_b32_e32 v1, v0, v1, vcc
	v_lshlrev_b32_e32 v99, 2, v1
	v_xor_b32_e32 v1, 32, v0
	v_cmp_lt_i32_e32 vcc, v1, v4
	v_lshlrev_b32_e32 v90, 3, v2
	v_lshl_add_u64 v[94:95], s[64:65], 0, v[162:163]
	v_cndmask_b32_e32 v0, v0, v1, vcc
	v_lshlrev_b32_e32 v138, 2, v0
	v_or_b32_e32 v0, v3, v139
	v_lshlrev_b32_e32 v140, 2, v0
	v_or_b32_e32 v141, 4, v140
	v_or_b32_e32 v142, 8, v140
	v_or_b32_e32 v143, 12, v140
	s_mov_b64 s[60:61], 0
	v_lshlrev_b32_e32 v96, 1, v88
	s_branch .LBB0_361
; __device__ __forceinline__ bf16_t f2bf(float f) { unsigned u = __float_as_uint(f); u += 0x7FFFu + ((u >> 16) & 1u); return (bf16_t)(u >> 16); }
; __device__ __forceinline__ float bf2f(bf16_t b) { return __uint_as_float(((unsigned)b) << 16); }
; __device__ void attn_phase(PP p, int layer) {
;     ...
;     for (int task = blockIdx.x * 8 + wid; task < ntask; task += gridDim.x * 8) {
;     ...
;         float ltot = lrun + __shfl_xor(lrun, 16); ltot += __shfl_xor(ltot, 32);
;         const float inv = 1.0f / ltot;
; #pragma unroll
;         for (int jj = 0; jj < 4; ++jj) { const float ij = __shfl(inv, quad * 4 + jj); const int tok = tq0 + quad * 4 + jj;
; #pragma unroll
;             for (int dt = 0; dt < 4; ++dt) { const int d = dt * 16 + qi; const float z = bf2f(PROJ[(size_t)tok * NIN + 1536 + head * 64 + d]);
;                 U[(size_t)tok * DM + head * 64 + d] = f2bf(O[dt][jj] * ij * z); } }
;     }
.LBB0_360:
	s_or_b64 exec, exec, s[62:63]
	ds_bpermute_b32 v16, v99, v24
	v_lshlrev_b32_e32 v162, 1, v98
	s_waitcnt lgkmcnt(0)
	v_add_f32_e32 v16, v24, v16
	ds_bpermute_b32 v17, v138, v16
	s_waitcnt lgkmcnt(0)
	v_add_f32_e32 v16, v16, v17
	v_div_scale_f32 v17, s[6:7], v16, v16, 1.0
	v_rcp_f32_e32 v18, v17
	s_nop 0
	v_fma_f32 v19, -v17, v18, 1.0
	v_fmac_f32_e32 v18, v19, v18
	v_div_scale_f32 v19, vcc, 1.0, v16, 1.0
	v_mul_f32_e32 v20, v19, v18
	v_fma_f32 v21, -v17, v20, v19
	v_fmac_f32_e32 v20, v21, v18
	v_fma_f32 v17, -v17, v20, v19
	v_div_fmas_f32 v17, v17, v18, v20
	v_add_u32_e32 v20, v97, v139
	v_lshl_add_u64 v[18:19], s[64:65], 0, v[162:163]
	v_mad_i64_i32 v[22:23], s[6:7], v20, s68, v[18:19]
	v_mov_b32_e32 v97, v163
	v_ashrrev_i32_e32 v21, 31, v20
	v_lshl_add_u64 v[22:23], v[22:23], 0, v[96:97]
	v_lshlrev_b64 v[24:25], 12, v[20:21]
	global_load_ushort v210, v[22:23], off offset:3072
	global_load_ushort v211, v[22:23], off offset:3104
	global_load_ushort v212, v[22:23], off offset:3136
	global_load_ushort v213, v[22:23], off offset:3168
	s_mov_b64 s[6:7], 0x7000
	s_nop 0
	v_lshl_add_u64 v[226:227], v[22:23], 0, s[6:7]
	global_load_ushort v214, v[226:227], off offset:3072
	global_load_ushort v215, v[226:227], off offset:3104
	global_load_ushort v216, v[226:227], off offset:3136
	global_load_ushort v217, v[226:227], off offset:3168
	s_mov_b64 s[6:7], 0xe000
	s_nop 0
	v_lshl_add_u64 v[226:227], v[22:23], 0, s[6:7]
	global_load_ushort v218, v[226:227], off offset:3072
	global_load_ushort v219, v[226:227], off offset:3104
	global_load_ushort v220, v[226:227], off offset:3136
	global_load_ushort v221, v[226:227], off offset:3168
	s_mov_b64 s[6:7], 0x15000
	s_nop 0
	v_lshl_add_u64 v[226:227], v[22:23], 0, s[6:7]
	global_load_ushort v222, v[226:227], off offset:3072
	global_load_ushort v223, v[226:227], off offset:3104
	global_load_ushort v224, v[226:227], off offset:3136
	global_load_ushort v225, v[226:227], off offset:3168
	v_div_fixup_f32 v26, v17, v16, 1.0
	ds_bpermute_b32 v27, v140, v26
	v_lshl_add_u64 v[16:17], s[48:49], 0, v[162:163]
	v_lshl_add_u64 v[24:25], v[16:17], 0, v[24:25]
	v_lshl_add_u64 v[24:25], v[24:25], 0, v[96:97]
	s_waitcnt lgkmcnt(0)
	v_mul_f32_e32 v12, v12, v27
	v_mul_f32_e32 v8, v8, v27
	v_mul_f32_e32 v4, v4, v27
	v_mul_f32_e32 v0, v0, v27
	s_waitcnt vmcnt(0)
	v_mov_b32_e32 v21, v210
	v_lshlrev_b32_e32 v21, 16, v21
	v_mul_f32_e32 v12, v12, v21
	v_bfe_u32 v21, v12, 16, 1
	v_add3_u32 v12, v12, v21, s69
	global_store_short_d16_hi v[24:25], v12, off
	v_mov_b32_e32 v12, v211
	s_nop 0
	v_lshlrev_b32_e32 v12, 16, v12
	v_mul_f32_e32 v8, v8, v12
	v_bfe_u32 v12, v8, 16, 1
	v_add3_u32 v8, v8, v12, s69
	global_store_short_d16_hi v[24:25], v8, off offset:32
	v_mov_b32_e32 v8, v212
	s_nop 0
	v_lshlrev_b32_e32 v8, 16, v8
	v_mul_f32_e32 v4, v4, v8
	v_bfe_u32 v8, v4, 16, 1
	v_add3_u32 v4, v4, v8, s69
	global_store_short_d16_hi v[24:25], v4, off offset:64
	v_mov_b32_e32 v4, v213
	v_add_u32_e32 v22, 1, v20
	v_ashrrev_i32_e32 v23, 31, v22
	s_nop 0
	v_lshlrev_b32_e32 v4, 16, v4
	v_mul_f32_e32 v0, v0, v4
	v_bfe_u32 v4, v0, 16, 1
	v_add3_u32 v0, v0, v4, s69
	global_store_short_d16_hi v[24:25], v0, off offset:96
	v_mad_i64_i32 v[24:25], s[6:7], v22, s68, v[18:19]
	v_lshl_add_u64 v[24:25], v[24:25], 0, v[96:97]
	v_mov_b32_e32 v4, v214
	ds_bpermute_b32 v0, v141, v26
	v_lshlrev_b64 v[22:23], 12, v[22:23]
	v_lshl_add_u64 v[22:23], v[16:17], 0, v[22:23]
	s_waitcnt lgkmcnt(0)
	v_mul_f32_e32 v8, v13, v0
	v_lshl_add_u64 v[12:13], v[22:23], 0, v[96:97]
	v_mul_f32_e32 v5, v5, v0
	s_nop 0
	v_lshlrev_b32_e32 v4, 16, v4
	v_mul_f32_e32 v4, v8, v4
	v_bfe_u32 v8, v4, 16, 1
	v_add3_u32 v4, v4, v8, s69
	global_store_short_d16_hi v[12:13], v4, off
	v_mov_b32_e32 v4, v215
	v_mul_f32_e32 v8, v9, v0
	v_mul_f32_e32 v0, v1, v0
	s_nop 0
	v_lshlrev_b32_e32 v4, 16, v4
	v_mul_f32_e32 v4, v8, v4
	v_bfe_u32 v8, v4, 16, 1
	v_add3_u32 v4, v4, v8, s69
	global_store_short_d16_hi v[12:13], v4, off offset:32
	v_mov_b32_e32 v4, v216
	ds_bpermute_b32 v8, v142, v26
	s_waitcnt lgkmcnt(0)
	v_mul_f32_e32 v10, v10, v8
	v_mul_f32_e32 v6, v6, v8
	v_mul_f32_e32 v2, v2, v8
	s_nop 0
	v_lshlrev_b32_e32 v4, 16, v4
	v_mul_f32_e32 v4, v5, v4
	v_bfe_u32 v5, v4, 16, 1
	v_add3_u32 v4, v4, v5, s69
	global_store_short_d16_hi v[12:13], v4, off offset:64
	v_mov_b32_e32 v4, v217
	s_nop 0
	v_lshlrev_b32_e32 v4, 16, v4
	v_mul_f32_e32 v0, v0, v4
	v_bfe_u32 v1, v0, 16, 1
	v_add3_u32 v0, v0, v1, s69
	global_store_short_d16_hi v[12:13], v0, off offset:96
	v_add_u32_e32 v0, 2, v20
	v_mad_i64_i32 v[4:5], s[6:7], v0, s68, v[18:19]
	v_lshl_add_u64 v[4:5], v[4:5], 0, v[96:97]
	v_mov_b32_e32 v9, v218
	v_ashrrev_i32_e32 v1, 31, v0
	v_mul_f32_e32 v12, v14, v8
	v_lshlrev_b64 v[0:1], 12, v[0:1]
	v_lshl_add_u64 v[0:1], v[16:17], 0, v[0:1]
	v_lshl_add_u64 v[0:1], v[0:1], 0, v[96:97]
	s_nop 0
	v_lshlrev_b32_e32 v9, 16, v9
	v_mul_f32_e32 v9, v12, v9
	v_bfe_u32 v12, v9, 16, 1
	v_add3_u32 v9, v9, v12, s69
	global_store_short_d16_hi v[0:1], v9, off
	v_mov_b32_e32 v9, v219
	s_nop 0
	v_lshlrev_b32_e32 v9, 16, v9
	v_mul_f32_e32 v9, v10, v9
	v_bfe_u32 v10, v9, 16, 1
	v_add3_u32 v9, v9, v10, s69
	global_store_short_d16_hi v[0:1], v9, off offset:32
	v_mov_b32_e32 v9, v220
	s_nop 0
	v_lshlrev_b32_e32 v9, 16, v9
	v_mov_b32_e32 v4, v221
	v_mul_f32_e32 v6, v6, v9
	v_bfe_u32 v9, v6, 16, 1
	v_add3_u32 v6, v6, v9, s69
	global_store_short_d16_hi v[0:1], v6, off offset:64
	s_nop 0
	v_lshlrev_b32_e32 v4, 16, v4
	v_mul_f32_e32 v2, v2, v4
	v_bfe_u32 v4, v2, 16, 1
	v_add3_u32 v2, v2, v4, s69
	global_store_short_d16_hi v[0:1], v2, off offset:96
	v_add_u32_e32 v0, 3, v20
	v_mad_i64_i32 v[4:5], s[6:7], v0, s68, v[18:19]
	v_lshl_add_u64 v[4:5], v[4:5], 0, v[96:97]
	v_mov_b32_e32 v6, v222
	ds_bpermute_b32 v2, v143, v26
	v_ashrrev_i32_e32 v1, 31, v0
	v_lshlrev_b64 v[0:1], 12, v[0:1]
	v_lshl_add_u64 v[0:1], v[16:17], 0, v[0:1]
	v_lshl_add_u64 v[0:1], v[0:1], 0, v[96:97]
	s_waitcnt lgkmcnt(0)
	v_mul_f32_e32 v8, v15, v2
	v_mul_f32_e32 v7, v7, v2
	v_readlane_b32 s6, v249, 26
	s_nop 0
	v_lshlrev_b32_e32 v6, 16, v6
	v_mul_f32_e32 v6, v8, v6
	v_bfe_u32 v8, v6, 16, 1
	v_add3_u32 v6, v6, v8, s69
	global_store_short_d16_hi v[0:1], v6, off
	v_mov_b32_e32 v6, v223
	v_mul_f32_e32 v8, v11, v2
	v_mul_f32_e32 v2, v3, v2
	v_add_u32_e32 v89, s6, v89
	v_cmp_lt_u32_e32 vcc, 0x21ff, v89
	s_nop 1
	v_cndmask_b32_e32 v231, 0, v230, vcc
	v_sub_u32_e32 v89, v89, v231
	v_cmp_le_i32_e32 vcc, s4, v89
	s_or_b64 s[60:61], vcc, s[60:61]
	s_nop 0
	v_lshlrev_b32_e32 v6, 16, v6
	v_mul_f32_e32 v6, v8, v6
	v_bfe_u32 v8, v6, 16, 1
	v_add3_u32 v6, v6, v8, s69
	global_store_short_d16_hi v[0:1], v6, off offset:32
	v_mov_b32_e32 v6, v224
	s_nop 0
	v_lshlrev_b32_e32 v6, 16, v6
	v_mov_b32_e32 v4, v225
	v_mul_f32_e32 v6, v7, v6
	v_bfe_u32 v7, v6, 16, 1
	v_add3_u32 v6, v6, v7, s69
	global_store_short_d16_hi v[0:1], v6, off offset:64
	s_nop 0
	v_lshlrev_b32_e32 v4, 16, v4
	v_mul_f32_e32 v2, v2, v4
	v_bfe_u32 v3, v2, 16, 1
	v_add3_u32 v2, v2, v3, s69
	global_store_short_d16_hi v[0:1], v2, off offset:96
	s_andn2_b64 exec, exec, s[60:61]
	s_cbranch_execz .LBB0_403
